# grid barriers: agent-scope acquire (L1 invalidate) issued by wave 1 at workgroup arrival, overlapping the arrive/poll sequence, instead of after the release is observed
# speedup vs baseline: 1.0089x; 1.0089x over previous
.LBB0_256:
.LBB0_257:
	s_or_b64 exec, exec, s[2:3]
.LBB0_258:
	v_mov_b32_e32 v0, 0
	s_cmp_lg_u32 s94, 64
	s_cbranch_scc1 .Lginv_0
	buffer_inv sc1
	s_waitcnt vmcnt(0)
.Lginv_0:
	s_barrier
	s_getreg_b32 s0, hwreg(HW_REG_XCC_ID, 0, 4)
	global_load_dword v0, v0, s[96:97] sc1
	v_mov_b32_e32 v1, 0x48000
	global_load_dword v2, v1, s[86:87] offset:1536 sc1
	global_load_dword v3, v1, s[86:87] offset:1792 sc1
	global_load_dword v4, v1, s[86:87] offset:2048 sc1
	global_load_dword v5, v1, s[86:87] offset:2304 sc1
	global_load_dword v6, v1, s[86:87] offset:2560 sc1
	global_load_dword v7, v1, s[86:87] offset:2816 sc1
	global_load_dword v8, v1, s[86:87] offset:3072 sc1
	global_load_dword v9, v1, s[86:87] offset:3328 sc1
	global_load_dword v10, v1, s[86:87] offset:3584 sc1
	s_nop 0
	global_load_dword v1, v1, s[86:87] offset:3840 sc1
	v_mov_b32_e32 v11, 0x49000
	global_load_dword v12, v11, s[86:87] sc1
	global_load_dword v13, v11, s[86:87] offset:256 sc1
	global_load_dword v14, v11, s[86:87] offset:512 sc1
	global_load_dword v15, v11, s[86:87] offset:768 sc1
	s_and_b32 s0, s0, 15
	global_load_dword v11, v11, s[86:87] offset:1024 sc1
	s_cmp_eq_u32 s0, 0
	s_cselect_b64 vcc, -1, 0
	s_cmp_eq_u32 s0, 1
	v_writelane_b32 v245, s0, 50
	s_waitcnt vmcnt(15)
	v_cmp_ne_u32_e64 s[2:3], 0, v0
	s_nop 1
	v_cndmask_b32_e64 v16, 0, 1, s[2:3]
	s_waitcnt vmcnt(13)
	v_cmp_ne_u32_e64 s[2:3], 0, v3
	v_cndmask_b32_e32 v0, 0, v0, vcc
	s_cselect_b64 vcc, -1, 0
	v_cndmask_b32_e64 v17, 0, 1, s[2:3]
	s_waitcnt vmcnt(11)
	v_cmp_ne_u32_e64 s[2:3], 0, v5
	s_cmp_eq_u32 s0, 2
	v_cndmask_b32_e32 v0, v0, v2, vcc
	v_cndmask_b32_e64 v18, 0, 1, s[2:3]
	s_waitcnt vmcnt(9)
	v_cmp_ne_u32_e64 s[2:3], 0, v7
	s_cselect_b64 vcc, -1, 0
	v_cndmask_b32_e32 v0, v0, v3, vcc
	v_cndmask_b32_e64 v19, 0, 1, s[2:3]
	s_waitcnt vmcnt(7)
	v_cmp_ne_u32_e64 s[2:3], 0, v9
	v_cmp_ne_u32_e32 vcc, 0, v4
	s_cmp_eq_u32 s0, 3
	v_cndmask_b32_e64 v20, 0, 1, s[2:3]
	s_waitcnt vmcnt(5)
	v_cmp_ne_u32_e64 s[2:3], 0, v1
	s_nop 1
	v_cndmask_b32_e64 v21, 0, 1, s[2:3]
	s_waitcnt vmcnt(3)
	v_cmp_ne_u32_e64 s[2:3], 0, v13
	s_nop 1
	v_cndmask_b32_e64 v22, 0, 1, s[2:3]
	v_cmp_ne_u32_e64 s[2:3], 0, v2
	s_nop 1
	v_addc_co_u32_e64 v16, s[2:3], 0, v16, s[2:3]
	v_addc_co_u32_e32 v2, vcc, v16, v17, vcc
	s_cselect_b64 vcc, -1, 0
	s_cmp_eq_u32 s0, 4
	v_cndmask_b32_e32 v0, v0, v4, vcc
	s_cselect_b64 vcc, -1, 0
	s_cmp_eq_u32 s0, 5
	v_cndmask_b32_e32 v0, v0, v5, vcc
	s_cselect_b64 vcc, -1, 0
	s_cmp_eq_u32 s0, 6
	v_cmp_ne_u32_e64 s[2:3], 0, v6
	v_cndmask_b32_e32 v0, v0, v6, vcc
	s_cselect_b64 vcc, -1, 0
	s_cmp_eq_u32 s0, 7
	v_addc_co_u32_e64 v2, s[2:3], v2, v18, s[2:3]
	v_cndmask_b32_e32 v0, v0, v7, vcc
	s_cselect_b64 vcc, -1, 0
	s_cmp_eq_u32 s0, 8
	v_cmp_ne_u32_e64 s[2:3], 0, v8
	v_cndmask_b32_e32 v0, v0, v8, vcc
	s_cselect_b64 vcc, -1, 0
	s_cmp_eq_u32 s0, 9
	v_addc_co_u32_e64 v2, s[2:3], v2, v19, s[2:3]
	v_cndmask_b32_e32 v0, v0, v9, vcc
	s_cselect_b64 vcc, -1, 0
	s_cmp_eq_u32 s0, 10
	v_cmp_ne_u32_e64 s[2:3], 0, v10
	v_cndmask_b32_e32 v0, v0, v10, vcc
	s_cselect_b64 vcc, -1, 0
	s_cmp_eq_u32 s0, 11
	v_addc_co_u32_e64 v2, s[2:3], v2, v20, s[2:3]
	v_cndmask_b32_e32 v0, v0, v1, vcc
	s_cselect_b64 vcc, -1, 0
	s_cmp_eq_u32 s0, 12
	v_cmp_ne_u32_e64 s[2:3], 0, v12
	v_cndmask_b32_e32 v0, v0, v12, vcc
	s_cselect_b64 vcc, -1, 0
	v_addc_co_u32_e64 v2, s[2:3], v2, v21, s[2:3]
	v_cndmask_b32_e32 v0, v0, v13, vcc
	s_waitcnt vmcnt(2)
	v_cmp_ne_u32_e32 vcc, 0, v14
	s_cmp_eq_u32 s0, 13
	s_nop 0
	v_addc_co_u32_e32 v1, vcc, v2, v22, vcc
	s_cselect_b64 vcc, -1, 0
	s_nop 0
	v_cndmask_b32_e32 v0, v0, v14, vcc
	s_waitcnt vmcnt(1)
	v_cmp_ne_u32_e32 vcc, 0, v15
	s_cmp_eq_u32 s0, 14
	s_nop 0
	v_cndmask_b32_e64 v2, 0, 1, vcc
	s_cselect_b64 vcc, -1, 0
	v_cndmask_b32_e32 v0, v0, v15, vcc
	s_waitcnt vmcnt(0)
	v_cmp_ne_u32_e32 vcc, 0, v11
	s_cmp_eq_u32 s0, 15
	s_nop 0
	v_addc_co_u32_e32 v1, vcc, v1, v2, vcc
	s_cselect_b64 vcc, -1, 0
	s_nop 0
	v_cndmask_b32_e32 v0, v0, v11, vcc
	s_nop 0
	v_readfirstlane_b32 s0, v0
	s_nop 1
	v_writelane_b32 v245, s0, 51
	v_readfirstlane_b32 s0, v1
	s_nop 1
	v_writelane_b32 v245, s0, 52

.LBB0_276:
	s_cmp_lg_u32 s94, 64
	s_cbranch_scc1 .Lginv_1
	buffer_inv sc1
	s_waitcnt vmcnt(0)

.LBB0_300:
.LBB0_301:
	s_or_b64 exec, exec, s[4:5]
